# th13 with the three K-loop heads aligned to 64 bytes
# baseline (speedup 1.0000x reference)
.LBB0_255:
	s_ashr_i32 s17, s16, 31
	s_lshl_b64 s[8:9], s[16:17], 20
	v_readlane_b32 s18, v254, 39
	v_readlane_b32 s19, v254, 40
	s_add_u32 s18, s18, s8
	s_addc_u32 s19, s19, s9
	s_and_b64 s[8:9], s[36:37], exec
	s_cselect_b32 s8, s19, s3
	s_cselect_b32 s9, s18, s2
	s_ashr_i32 s15, s14, 31
	s_lshl_b64 s[20:21], s[14:15], 20
	s_add_u32 s20, s29, s20
	s_addc_u32 s21, s38, s21
	s_and_b64 s[26:27], s[36:37], exec
	s_cselect_b32 s15, s21, s23
	s_cselect_b32 s17, s20, s22
	s_add_u32 s2, s2, 0x80800
	s_addc_u32 s3, s3, 0
	s_add_u32 s33, s22, 0x100
	s_addc_u32 s34, s23, 0
	s_mov_b32 s35, -2
	s_add_u32 s22, s2, 0xfff80800
	s_addc_u32 s23, s3, -1
	s_add_i32 s48, 0, 0x10000
	s_cmp_eq_u32 s35, 28
	s_cselect_b32 s27, s8, s23
	s_cselect_b32 s26, s9, s22
	s_cselect_b32 s23, s15, s34
	s_cselect_b32 s22, s17, s33
	s_add_i32 s50, 0, 0x14000
	v_add_u32_e32 v176, s48, v191
	v_add_u32_e32 v188, s50, v191
	ds_read_b128 v[148:151], v176
	ds_read_b128 v[152:155], v176 offset:1024
	ds_read_b128 v[172:175], v176 offset:2048
	ds_read_b128 v[176:179], v176 offset:3072
	ds_read_b128 v[180:183], v188
	ds_read_b128 v[184:187], v188 offset:1024
	ds_read_b128 v[196:199], v188 offset:2048
	ds_read_b128 v[200:203], v188 offset:3072
	s_add_i32 m0, s39, 0xc000
	ds_read_b128 v[204:207], v194
	ds_read_b128 v[212:215], v194 offset:1024
	ds_read_b128 v[216:219], v194 offset:2048
	ds_read_b128 v[220:223], v194 offset:3072
	ds_read_b128 v[224:227], v194 offset:4096
	ds_read_b128 v[228:231], v194 offset:5120
	ds_read_b128 v[232:235], v194 offset:6144
	ds_read_b128 v[236:239], v194 offset:7168
	global_load_lds_dwordx4 v168, s[2:3]
	s_add_i32 m0, s39, 0xe000
	s_nop 0
	global_load_lds_dwordx4 v170, s[2:3]
	s_waitcnt vmcnt(8)
	s_waitcnt lgkmcnt(0)
	s_setprio 1
	s_barrier
	v_mfma_f32_16x16x32_bf16 v[144:147], v[148:151], v[204:207], 0
	v_mfma_f32_16x16x32_bf16 v[136:139], v[172:175], v[204:207], 0
	v_mfma_f32_16x16x32_bf16 v[128:131], v[148:151], v[216:219], 0
	v_mfma_f32_16x16x32_bf16 v[120:123], v[172:175], v[216:219], 0
	v_mfma_f32_16x16x32_bf16 v[112:115], v[148:151], v[224:227], 0
	v_mfma_f32_16x16x32_bf16 v[104:107], v[172:175], v[224:227], 0
	v_mfma_f32_16x16x32_bf16 v[96:99], v[148:151], v[232:235], 0
	v_mfma_f32_16x16x32_bf16 v[88:91], v[172:175], v[232:235], 0
	v_mfma_f32_16x16x32_bf16 v[144:147], v[152:155], v[212:215], v[144:147]
	v_mfma_f32_16x16x32_bf16 v[136:139], v[176:179], v[212:215], v[136:139]
	v_mfma_f32_16x16x32_bf16 v[128:131], v[152:155], v[220:223], v[128:131]
	v_mfma_f32_16x16x32_bf16 v[120:123], v[176:179], v[220:223], v[120:123]
	v_mfma_f32_16x16x32_bf16 v[112:115], v[152:155], v[228:231], v[112:115]
	v_mfma_f32_16x16x32_bf16 v[104:107], v[176:179], v[228:231], v[104:107]
	v_mfma_f32_16x16x32_bf16 v[96:99], v[152:155], v[236:239], v[96:99]
	v_mfma_f32_16x16x32_bf16 v[88:91], v[176:179], v[236:239], v[88:91]
	v_mfma_f32_16x16x32_bf16 v[140:143], v[180:183], v[204:207], 0
	v_mfma_f32_16x16x32_bf16 v[132:135], v[196:199], v[204:207], 0
	v_mfma_f32_16x16x32_bf16 v[124:127], v[180:183], v[216:219], 0
	v_mfma_f32_16x16x32_bf16 v[116:119], v[196:199], v[216:219], 0
	v_mfma_f32_16x16x32_bf16 v[108:111], v[180:183], v[224:227], 0
	v_mfma_f32_16x16x32_bf16 v[100:103], v[196:199], v[224:227], 0
	v_mfma_f32_16x16x32_bf16 v[92:95], v[180:183], v[232:235], 0
	v_mfma_f32_16x16x32_bf16 v[84:87], v[196:199], v[232:235], 0
	v_mfma_f32_16x16x32_bf16 v[140:143], v[184:187], v[212:215], v[140:143]
	v_mfma_f32_16x16x32_bf16 v[132:135], v[200:203], v[212:215], v[132:135]
	v_mfma_f32_16x16x32_bf16 v[124:127], v[184:187], v[220:223], v[124:127]
	v_mfma_f32_16x16x32_bf16 v[116:119], v[200:203], v[220:223], v[116:119]
	v_mfma_f32_16x16x32_bf16 v[108:111], v[184:187], v[228:231], v[108:111]
	v_mfma_f32_16x16x32_bf16 v[100:103], v[200:203], v[228:231], v[100:103]
	v_mfma_f32_16x16x32_bf16 v[92:95], v[184:187], v[236:239], v[92:95]
	v_mfma_f32_16x16x32_bf16 v[84:87], v[200:203], v[236:239], v[84:87]
	s_barrier
	s_setprio 0
	s_add_i32 s48, s48, s28
	s_add_u32 s98, s22, 0x80
	s_addc_u32 s99, s23, 0
	s_add_u32 s100, s26, 0x800
	s_addc_u32 s101, s27, 0
	s_mov_b32 m0, s48
	ds_read_b128 v[204:207], v194 offset:16384
	ds_read_b128 v[212:215], v194 offset:17408
	ds_read_b128 v[216:219], v194 offset:18432
	ds_read_b128 v[220:223], v194 offset:19456
	ds_read_b128 v[224:227], v194 offset:20480
	ds_read_b128 v[228:231], v194 offset:21504
	ds_read_b128 v[232:235], v194 offset:22528
	ds_read_b128 v[236:239], v194 offset:23552
	global_load_lds_dwordx4 v2, s[22:23]
	s_add_i32 m0, s48, 0x2000
	s_add_u32 s48, s22, 0x80000
	s_addc_u32 s49, s23, 0
	s_add_i32 s50, s50, s28
	global_load_lds_dwordx4 v156, s[22:23]
	s_mov_b32 m0, s50
	s_nop 0
	global_load_lds_dwordx4 v2, s[48:49]
	s_add_i32 m0, s50, 0x2000
	s_nop 0
	global_load_lds_dwordx4 v156, s[48:49]
	s_mov_b32 m0, s39
	s_nop 0
	global_load_lds_dwordx4 v160, s[26:27]
	s_mov_b32 m0, s41
	s_nop 0
	global_load_lds_dwordx4 v158, s[26:27]
	s_waitcnt vmcnt(8)
	s_waitcnt lgkmcnt(0)
	s_setprio 1
	s_barrier
	v_mfma_f32_16x16x32_bf16 v[80:83], v[148:151], v[204:207], 0
	v_mfma_f32_16x16x32_bf16 v[72:75], v[172:175], v[204:207], 0
	v_mfma_f32_16x16x32_bf16 v[64:67], v[148:151], v[216:219], 0
	v_mfma_f32_16x16x32_bf16 v[56:59], v[172:175], v[216:219], 0
	v_mfma_f32_16x16x32_bf16 v[48:51], v[148:151], v[224:227], 0
	v_mfma_f32_16x16x32_bf16 v[40:43], v[172:175], v[224:227], 0
	v_mfma_f32_16x16x32_bf16 v[32:35], v[148:151], v[232:235], 0
	v_mfma_f32_16x16x32_bf16 v[24:27], v[172:175], v[232:235], 0
	v_mfma_f32_16x16x32_bf16 v[80:83], v[152:155], v[212:215], v[80:83]
	v_mfma_f32_16x16x32_bf16 v[72:75], v[176:179], v[212:215], v[72:75]
	v_mfma_f32_16x16x32_bf16 v[64:67], v[152:155], v[220:223], v[64:67]
	v_mfma_f32_16x16x32_bf16 v[56:59], v[176:179], v[220:223], v[56:59]
	v_mfma_f32_16x16x32_bf16 v[48:51], v[152:155], v[228:231], v[48:51]
	v_mfma_f32_16x16x32_bf16 v[40:43], v[176:179], v[228:231], v[40:43]
	v_mfma_f32_16x16x32_bf16 v[32:35], v[152:155], v[236:239], v[32:35]
	v_mfma_f32_16x16x32_bf16 v[24:27], v[176:179], v[236:239], v[24:27]
	v_mfma_f32_16x16x32_bf16 v[76:79], v[180:183], v[204:207], 0
	v_mfma_f32_16x16x32_bf16 v[68:71], v[196:199], v[204:207], 0
	v_mfma_f32_16x16x32_bf16 v[60:63], v[180:183], v[216:219], 0
	v_mfma_f32_16x16x32_bf16 v[52:55], v[196:199], v[216:219], 0
	v_mfma_f32_16x16x32_bf16 v[44:47], v[180:183], v[224:227], 0
	v_mfma_f32_16x16x32_bf16 v[36:39], v[196:199], v[224:227], 0
	v_mfma_f32_16x16x32_bf16 v[28:31], v[180:183], v[232:235], 0
	v_mfma_f32_16x16x32_bf16 v[20:23], v[196:199], v[232:235], 0
	v_mfma_f32_16x16x32_bf16 v[76:79], v[184:187], v[212:215], v[76:79]
	v_mfma_f32_16x16x32_bf16 v[68:71], v[200:203], v[212:215], v[68:71]
	v_mfma_f32_16x16x32_bf16 v[60:63], v[184:187], v[220:223], v[60:63]
	v_mfma_f32_16x16x32_bf16 v[52:55], v[200:203], v[220:223], v[52:55]
	v_mfma_f32_16x16x32_bf16 v[44:47], v[184:187], v[228:231], v[44:47]
	v_mfma_f32_16x16x32_bf16 v[36:39], v[200:203], v[228:231], v[36:39]
	v_mfma_f32_16x16x32_bf16 v[28:31], v[184:187], v[236:239], v[28:31]
	v_mfma_f32_16x16x32_bf16 v[20:23], v[200:203], v[236:239], v[20:23]
	s_barrier
	s_setprio 0
	s_add_i32 s48, 0, 0x18000
	s_add_i32 s49, 0, 0x1c000
	v_add_u32_e32 v176, s48, v191
	v_add_u32_e32 v195, s49, v191
	ds_read_b128 v[148:151], v176
	ds_read_b128 v[152:155], v176 offset:1024
	ds_read_b128 v[172:175], v176 offset:2048
	ds_read_b128 v[176:179], v176 offset:3072
	ds_read_b128 v[180:183], v195
	ds_read_b128 v[184:187], v195 offset:1024
	ds_read_b128 v[196:199], v195 offset:2048
	ds_read_b128 v[200:203], v195 offset:3072
	s_add_u32 s26, s26, 0x80000
	s_addc_u32 s27, s27, 0
	s_mov_b32 m0, s42
	ds_read_b128 v[204:207], v194 offset:32768
	ds_read_b128 v[212:215], v194 offset:33792
	ds_read_b128 v[216:219], v194 offset:34816
	ds_read_b128 v[220:223], v194 offset:35840
	ds_read_b128 v[224:227], v194 offset:36864
	ds_read_b128 v[228:231], v194 offset:37888
	ds_read_b128 v[232:235], v194 offset:38912
	ds_read_b128 v[236:239], v194 offset:39936
	global_load_lds_dwordx4 v160, s[26:27]
	s_mov_b32 m0, s43
	s_nop 0
	global_load_lds_dwordx4 v158, s[26:27]
	s_waitcnt vmcnt(8)
	s_waitcnt lgkmcnt(0)
	s_setprio 1
	s_barrier
	v_mfma_f32_16x16x32_bf16 v[144:147], v[148:151], v[204:207], v[144:147]
	v_mfma_f32_16x16x32_bf16 v[136:139], v[172:175], v[204:207], v[136:139]
	v_mfma_f32_16x16x32_bf16 v[128:131], v[148:151], v[216:219], v[128:131]
	v_mfma_f32_16x16x32_bf16 v[120:123], v[172:175], v[216:219], v[120:123]
	v_mfma_f32_16x16x32_bf16 v[112:115], v[148:151], v[224:227], v[112:115]
	v_mfma_f32_16x16x32_bf16 v[104:107], v[172:175], v[224:227], v[104:107]
	v_mfma_f32_16x16x32_bf16 v[96:99], v[148:151], v[232:235], v[96:99]
	v_mfma_f32_16x16x32_bf16 v[88:91], v[172:175], v[232:235], v[88:91]
	v_mfma_f32_16x16x32_bf16 v[144:147], v[152:155], v[212:215], v[144:147]
	v_mfma_f32_16x16x32_bf16 v[136:139], v[176:179], v[212:215], v[136:139]
	v_mfma_f32_16x16x32_bf16 v[128:131], v[152:155], v[220:223], v[128:131]
	v_mfma_f32_16x16x32_bf16 v[120:123], v[176:179], v[220:223], v[120:123]
	v_mfma_f32_16x16x32_bf16 v[112:115], v[152:155], v[228:231], v[112:115]
	v_mfma_f32_16x16x32_bf16 v[104:107], v[176:179], v[228:231], v[104:107]
	v_mfma_f32_16x16x32_bf16 v[96:99], v[152:155], v[236:239], v[96:99]
	v_mfma_f32_16x16x32_bf16 v[88:91], v[176:179], v[236:239], v[88:91]
	v_mfma_f32_16x16x32_bf16 v[140:143], v[180:183], v[204:207], v[140:143]
	v_mfma_f32_16x16x32_bf16 v[132:135], v[196:199], v[204:207], v[132:135]
	v_mfma_f32_16x16x32_bf16 v[124:127], v[180:183], v[216:219], v[124:127]
	v_mfma_f32_16x16x32_bf16 v[116:119], v[196:199], v[216:219], v[116:119]
	v_mfma_f32_16x16x32_bf16 v[108:111], v[180:183], v[224:227], v[108:111]
	v_mfma_f32_16x16x32_bf16 v[100:103], v[196:199], v[224:227], v[100:103]
	v_mfma_f32_16x16x32_bf16 v[92:95], v[180:183], v[232:235], v[92:95]
	v_mfma_f32_16x16x32_bf16 v[84:87], v[196:199], v[232:235], v[84:87]
	v_mfma_f32_16x16x32_bf16 v[140:143], v[184:187], v[212:215], v[140:143]
	v_mfma_f32_16x16x32_bf16 v[132:135], v[200:203], v[212:215], v[132:135]
	v_mfma_f32_16x16x32_bf16 v[124:127], v[184:187], v[220:223], v[124:127]
	v_mfma_f32_16x16x32_bf16 v[116:119], v[200:203], v[220:223], v[116:119]
	v_mfma_f32_16x16x32_bf16 v[108:111], v[184:187], v[228:231], v[108:111]
	v_mfma_f32_16x16x32_bf16 v[100:103], v[200:203], v[228:231], v[100:103]
	v_mfma_f32_16x16x32_bf16 v[92:95], v[184:187], v[236:239], v[92:95]
	v_mfma_f32_16x16x32_bf16 v[84:87], v[200:203], v[236:239], v[84:87]
	s_barrier
	s_setprio 0
	s_add_i32 s26, s48, s28
	s_mov_b32 m0, s26
	ds_read_b128 v[204:207], v194 offset:49152
	ds_read_b128 v[212:215], v194 offset:50176
	ds_read_b128 v[216:219], v194 offset:51200
	ds_read_b128 v[220:223], v194 offset:52224
	ds_read_b128 v[224:227], v194 offset:53248
	ds_read_b128 v[228:231], v194 offset:54272
	ds_read_b128 v[232:235], v194 offset:55296
	ds_read_b128 v[236:239], v194 offset:56320
	global_load_lds_dwordx4 v2, s[98:99]
	s_add_i32 m0, s26, 0x2000
	s_add_u32 s22, s22, 0x80080
	s_addc_u32 s23, s23, 0
	s_add_i32 s26, s49, s28
	global_load_lds_dwordx4 v156, s[98:99]
	s_mov_b32 m0, s26
	s_nop 0
	global_load_lds_dwordx4 v2, s[22:23]
	s_add_i32 m0, s26, 0x2000
	s_nop 0
	global_load_lds_dwordx4 v156, s[22:23]
	s_mov_b32 m0, s44
	s_nop 0
	global_load_lds_dwordx4 v160, s[100:101]
	s_mov_b32 m0, s45
	s_nop 0
	global_load_lds_dwordx4 v158, s[100:101]
	s_waitcnt vmcnt(8)
	s_waitcnt lgkmcnt(0)
	s_setprio 1
	s_barrier
	v_mfma_f32_16x16x32_bf16 v[80:83], v[148:151], v[204:207], v[80:83]
	v_mfma_f32_16x16x32_bf16 v[72:75], v[172:175], v[204:207], v[72:75]
	v_mfma_f32_16x16x32_bf16 v[64:67], v[148:151], v[216:219], v[64:67]
	v_mfma_f32_16x16x32_bf16 v[56:59], v[172:175], v[216:219], v[56:59]
	v_mfma_f32_16x16x32_bf16 v[48:51], v[148:151], v[224:227], v[48:51]
	v_mfma_f32_16x16x32_bf16 v[40:43], v[172:175], v[224:227], v[40:43]
	v_mfma_f32_16x16x32_bf16 v[32:35], v[148:151], v[232:235], v[32:35]
	v_mfma_f32_16x16x32_bf16 v[24:27], v[172:175], v[232:235], v[24:27]
	v_mfma_f32_16x16x32_bf16 v[80:83], v[152:155], v[212:215], v[80:83]
	v_mfma_f32_16x16x32_bf16 v[72:75], v[176:179], v[212:215], v[72:75]
	v_mfma_f32_16x16x32_bf16 v[64:67], v[152:155], v[220:223], v[64:67]
	v_mfma_f32_16x16x32_bf16 v[56:59], v[176:179], v[220:223], v[56:59]
	v_mfma_f32_16x16x32_bf16 v[48:51], v[152:155], v[228:231], v[48:51]
	v_mfma_f32_16x16x32_bf16 v[40:43], v[176:179], v[228:231], v[40:43]
	v_mfma_f32_16x16x32_bf16 v[32:35], v[152:155], v[236:239], v[32:35]
	v_mfma_f32_16x16x32_bf16 v[24:27], v[176:179], v[236:239], v[24:27]
	v_mfma_f32_16x16x32_bf16 v[76:79], v[180:183], v[204:207], v[76:79]
	v_mfma_f32_16x16x32_bf16 v[68:71], v[196:199], v[204:207], v[68:71]
	v_mfma_f32_16x16x32_bf16 v[60:63], v[180:183], v[216:219], v[60:63]
	v_mfma_f32_16x16x32_bf16 v[52:55], v[196:199], v[216:219], v[52:55]
	v_mfma_f32_16x16x32_bf16 v[44:47], v[180:183], v[224:227], v[44:47]
	v_mfma_f32_16x16x32_bf16 v[36:39], v[196:199], v[224:227], v[36:39]
	v_mfma_f32_16x16x32_bf16 v[28:31], v[180:183], v[232:235], v[28:31]
	v_mfma_f32_16x16x32_bf16 v[20:23], v[196:199], v[232:235], v[20:23]
	v_mfma_f32_16x16x32_bf16 v[76:79], v[184:187], v[212:215], v[76:79]
	v_mfma_f32_16x16x32_bf16 v[68:71], v[200:203], v[212:215], v[68:71]
	v_mfma_f32_16x16x32_bf16 v[60:63], v[184:187], v[220:223], v[60:63]
	v_mfma_f32_16x16x32_bf16 v[52:55], v[200:203], v[220:223], v[52:55]
	v_mfma_f32_16x16x32_bf16 v[44:47], v[184:187], v[228:231], v[44:47]
	v_mfma_f32_16x16x32_bf16 v[36:39], v[200:203], v[228:231], v[36:39]
	v_mfma_f32_16x16x32_bf16 v[28:31], v[184:187], v[236:239], v[28:31]
	v_mfma_f32_16x16x32_bf16 v[20:23], v[200:203], v[236:239], v[20:23]
	s_barrier
	s_setprio 0
	s_add_i32 s35, s35, 2
	s_add_u32 s2, s2, 0x1000
	s_addc_u32 s3, s3, 0
	s_add_u32 s33, s33, 0x100
	s_addc_u32 s34, s34, 0
	s_cmp_gt_u32 s35, 29
	s_cbranch_scc0 .LBB0_256
	s_branch .Lpeel_done_256
	.p2align	6

.LBB0_488:
	s_ashr_i32 s17, s16, 31
	s_lshl_b64 s[8:9], s[16:17], 20
	v_readlane_b32 s18, v254, 39
	v_readlane_b32 s19, v254, 40
	s_add_u32 s18, s18, s8
	s_addc_u32 s19, s19, s9
	s_and_b64 s[8:9], s[36:37], exec
	s_cselect_b32 s3, s19, s23
	s_cselect_b32 s6, s18, s22
	s_ashr_i32 s15, s14, 31
	s_lshl_b64 s[8:9], s[14:15], 20
	s_add_u32 s20, s28, s8
	s_addc_u32 s21, s29, s9
	s_and_b64 s[8:9], s[36:37], exec
	s_cselect_b32 s8, s21, s27
	s_cselect_b32 s9, s20, s26
	s_add_u32 s22, s22, 0x80800
	s_addc_u32 s23, s23, 0
	s_add_u32 s15, s26, 0x100
	s_addc_u32 s17, s27, 0
	s_mov_b32 s33, -2
	s_add_u32 s26, s22, 0xfff80800
	s_addc_u32 s27, s23, -1
	s_add_i32 s34, 0, 0x10000
	s_cmp_eq_u32 s33, 28
	s_cselect_b32 s39, s3, s27
	s_cselect_b32 s38, s6, s26
	s_cselect_b32 s27, s8, s17
	s_cselect_b32 s26, s9, s15
	s_add_i32 s53, 0, 0x14000
	v_add_u32_e32 v144, s34, v168
	v_add_u32_e32 v160, s53, v168
	ds_read_b128 v[4:7], v144
	ds_read_b128 v[8:11], v144 offset:1024
	ds_read_b128 v[140:143], v144 offset:2048
	ds_read_b128 v[144:147], v144 offset:3072
	ds_read_b128 v[172:175], v160
	ds_read_b128 v[176:179], v160 offset:1024
	ds_read_b128 v[180:183], v160 offset:2048
	ds_read_b128 v[184:187], v160 offset:3072
	s_add_i32 m0, s13, 0xc000
	ds_read_b128 v[188:191], v170
	ds_read_b128 v[192:195], v170 offset:1024
	ds_read_b128 v[196:199], v170 offset:2048
	ds_read_b128 v[200:203], v170 offset:3072
	ds_read_b128 v[204:207], v170 offset:4096
	ds_read_b128 v[212:215], v170 offset:5120
	ds_read_b128 v[216:219], v170 offset:6144
	ds_read_b128 v[220:223], v170 offset:7168
	global_load_lds_dwordx4 v156, s[22:23]
	s_add_i32 m0, s13, 0xe000
	s_nop 0
	global_load_lds_dwordx4 v158, s[22:23]
	s_waitcnt vmcnt(8)
	s_waitcnt lgkmcnt(0)
	s_setprio 1
	s_barrier
	v_mfma_f32_16x16x32_bf16 v[136:139], v[4:7], v[188:191], 0
	v_mfma_f32_16x16x32_bf16 v[132:135], v[140:143], v[188:191], 0
	v_mfma_f32_16x16x32_bf16 v[128:131], v[4:7], v[196:199], 0
	v_mfma_f32_16x16x32_bf16 v[120:123], v[140:143], v[196:199], 0
	v_mfma_f32_16x16x32_bf16 v[112:115], v[4:7], v[204:207], 0
	v_mfma_f32_16x16x32_bf16 v[104:107], v[140:143], v[204:207], 0
	v_mfma_f32_16x16x32_bf16 v[96:99], v[4:7], v[216:219], 0
	v_mfma_f32_16x16x32_bf16 v[88:91], v[140:143], v[216:219], 0
	v_mfma_f32_16x16x32_bf16 v[136:139], v[8:11], v[192:195], v[136:139]
	v_mfma_f32_16x16x32_bf16 v[132:135], v[144:147], v[192:195], v[132:135]
	v_mfma_f32_16x16x32_bf16 v[128:131], v[8:11], v[200:203], v[128:131]
	v_mfma_f32_16x16x32_bf16 v[120:123], v[144:147], v[200:203], v[120:123]
	v_mfma_f32_16x16x32_bf16 v[112:115], v[8:11], v[212:215], v[112:115]
	v_mfma_f32_16x16x32_bf16 v[104:107], v[144:147], v[212:215], v[104:107]
	v_mfma_f32_16x16x32_bf16 v[96:99], v[8:11], v[220:223], v[96:99]
	v_mfma_f32_16x16x32_bf16 v[88:91], v[144:147], v[220:223], v[88:91]
	v_mfma_f32_16x16x32_bf16 v[124:127], v[172:175], v[188:191], 0
	v_mfma_f32_16x16x32_bf16 v[116:119], v[180:183], v[188:191], 0
	v_mfma_f32_16x16x32_bf16 v[108:111], v[172:175], v[196:199], 0
	v_mfma_f32_16x16x32_bf16 v[100:103], v[180:183], v[196:199], 0
	v_mfma_f32_16x16x32_bf16 v[92:95], v[172:175], v[204:207], 0
	v_mfma_f32_16x16x32_bf16 v[84:87], v[180:183], v[204:207], 0
	v_mfma_f32_16x16x32_bf16 v[80:83], v[172:175], v[216:219], 0
	v_mfma_f32_16x16x32_bf16 v[76:79], v[180:183], v[216:219], 0
	v_mfma_f32_16x16x32_bf16 v[124:127], v[176:179], v[192:195], v[124:127]
	v_mfma_f32_16x16x32_bf16 v[116:119], v[184:187], v[192:195], v[116:119]
	v_mfma_f32_16x16x32_bf16 v[108:111], v[176:179], v[200:203], v[108:111]
	v_mfma_f32_16x16x32_bf16 v[100:103], v[184:187], v[200:203], v[100:103]
	v_mfma_f32_16x16x32_bf16 v[92:95], v[176:179], v[212:215], v[92:95]
	v_mfma_f32_16x16x32_bf16 v[84:87], v[184:187], v[212:215], v[84:87]
	v_mfma_f32_16x16x32_bf16 v[80:83], v[176:179], v[220:223], v[80:83]
	v_mfma_f32_16x16x32_bf16 v[76:79], v[184:187], v[220:223], v[76:79]
	s_barrier
	s_setprio 0
	s_add_i32 s34, s34, s7
	s_add_u32 s98, s26, 0x80
	s_addc_u32 s99, s27, 0
	s_add_u32 s100, s38, 0x800
	s_addc_u32 s101, s39, 0
	s_mov_b32 m0, s34
	ds_read_b128 v[188:191], v170 offset:16384
	ds_read_b128 v[192:195], v170 offset:17408
	ds_read_b128 v[196:199], v170 offset:18432
	ds_read_b128 v[200:203], v170 offset:19456
	ds_read_b128 v[204:207], v170 offset:20480
	ds_read_b128 v[212:215], v170 offset:21504
	ds_read_b128 v[216:219], v170 offset:22528
	ds_read_b128 v[220:223], v170 offset:23552
	global_load_lds_dwordx4 v2, s[26:27]
	s_add_i32 m0, s34, 0x2000
	s_add_u32 s34, s26, 0x80000
	s_addc_u32 s35, s27, 0
	s_add_i32 s53, s53, s7
	global_load_lds_dwordx4 v148, s[26:27]
	s_mov_b32 m0, s53
	s_nop 0
	global_load_lds_dwordx4 v2, s[34:35]
	s_add_i32 m0, s53, 0x2000
	s_nop 0
	global_load_lds_dwordx4 v148, s[34:35]
	s_mov_b32 m0, s13
	s_nop 0
	global_load_lds_dwordx4 v152, s[38:39]
	s_mov_b32 m0, s46
	s_nop 0
	global_load_lds_dwordx4 v150, s[38:39]
	s_waitcnt vmcnt(8)
	s_waitcnt lgkmcnt(0)
	s_setprio 1
	s_barrier
	v_mfma_f32_16x16x32_bf16 v[72:75], v[4:7], v[188:191], 0
	v_mfma_f32_16x16x32_bf16 v[68:71], v[140:143], v[188:191], 0
	v_mfma_f32_16x16x32_bf16 v[64:67], v[4:7], v[196:199], 0
	v_mfma_f32_16x16x32_bf16 v[56:59], v[140:143], v[196:199], 0
	v_mfma_f32_16x16x32_bf16 v[48:51], v[4:7], v[204:207], 0
	v_mfma_f32_16x16x32_bf16 v[40:43], v[140:143], v[204:207], 0
	v_mfma_f32_16x16x32_bf16 v[4:7], v[4:7], v[216:219], 0
	v_mfma_f32_16x16x32_bf16 v[72:75], v[8:11], v[192:195], v[72:75]
	v_mfma_f32_16x16x32_bf16 v[68:71], v[144:147], v[192:195], v[68:71]
	v_mfma_f32_16x16x32_bf16 v[64:67], v[8:11], v[200:203], v[64:67]
	v_mfma_f32_16x16x32_bf16 v[56:59], v[144:147], v[200:203], v[56:59]
	v_mfma_f32_16x16x32_bf16 v[48:51], v[8:11], v[212:215], v[48:51]
	v_mfma_f32_16x16x32_bf16 v[40:43], v[144:147], v[212:215], v[40:43]
	v_mfma_f32_16x16x32_bf16 v[4:7], v[8:11], v[220:223], v[4:7]
	v_mfma_f32_16x16x32_bf16 v[8:11], v[140:143], v[216:219], 0
	v_mfma_f32_16x16x32_bf16 v[8:11], v[144:147], v[220:223], v[8:11]
	v_mfma_f32_16x16x32_bf16 v[24:27], v[172:175], v[188:191], 0
	v_mfma_f32_16x16x32_bf16 v[60:63], v[176:179], v[192:195], v[24:27]
	v_mfma_f32_16x16x32_bf16 v[24:27], v[180:183], v[188:191], 0
	v_mfma_f32_16x16x32_bf16 v[52:55], v[184:187], v[192:195], v[24:27]
	v_mfma_f32_16x16x32_bf16 v[24:27], v[172:175], v[196:199], 0
	v_mfma_f32_16x16x32_bf16 v[44:47], v[176:179], v[200:203], v[24:27]
	v_mfma_f32_16x16x32_bf16 v[24:27], v[180:183], v[196:199], 0
	v_mfma_f32_16x16x32_bf16 v[36:39], v[184:187], v[200:203], v[24:27]
	v_mfma_f32_16x16x32_bf16 v[24:27], v[172:175], v[204:207], 0
	v_mfma_f32_16x16x32_bf16 v[20:23], v[180:183], v[204:207], 0
	v_mfma_f32_16x16x32_bf16 v[16:19], v[172:175], v[216:219], 0
	v_mfma_f32_16x16x32_bf16 v[12:15], v[180:183], v[216:219], 0
	v_mfma_f32_16x16x32_bf16 v[28:31], v[176:179], v[212:215], v[24:27]
	v_mfma_f32_16x16x32_bf16 v[20:23], v[184:187], v[212:215], v[20:23]
	v_mfma_f32_16x16x32_bf16 v[16:19], v[176:179], v[220:223], v[16:19]
	v_mfma_f32_16x16x32_bf16 v[12:15], v[184:187], v[220:223], v[12:15]
	s_barrier
	s_setprio 0
	s_add_i32 s53, 0, 0x18000
	s_add_i32 s54, 0, 0x1c000
	v_add_u32_e32 v144, s53, v168
	v_add_u32_e32 v171, s54, v168
	ds_read_b128 v[24:27], v144
	ds_read_b128 v[32:35], v144 offset:1024
	ds_read_b128 v[140:143], v144 offset:2048
	ds_read_b128 v[144:147], v144 offset:3072
	ds_read_b128 v[172:175], v171
	ds_read_b128 v[176:179], v171 offset:1024
	ds_read_b128 v[180:183], v171 offset:2048
	ds_read_b128 v[184:187], v171 offset:3072
	s_add_u32 s34, s38, 0x80000
	s_addc_u32 s35, s39, 0
	s_mov_b32 m0, s47
	ds_read_b128 v[188:191], v170 offset:32768
	ds_read_b128 v[192:195], v170 offset:33792
	ds_read_b128 v[196:199], v170 offset:34816
	ds_read_b128 v[200:203], v170 offset:35840
	ds_read_b128 v[204:207], v170 offset:36864
	ds_read_b128 v[212:215], v170 offset:37888
	ds_read_b128 v[216:219], v170 offset:38912
	ds_read_b128 v[220:223], v170 offset:39936
	global_load_lds_dwordx4 v152, s[34:35]
	s_mov_b32 m0, s48
	s_nop 0
	global_load_lds_dwordx4 v150, s[34:35]
	s_waitcnt vmcnt(8)
	s_waitcnt lgkmcnt(0)
	s_setprio 1
	s_barrier
	v_mfma_f32_16x16x32_bf16 v[136:139], v[24:27], v[188:191], v[136:139]
	v_mfma_f32_16x16x32_bf16 v[132:135], v[140:143], v[188:191], v[132:135]
	v_mfma_f32_16x16x32_bf16 v[128:131], v[24:27], v[196:199], v[128:131]
	v_mfma_f32_16x16x32_bf16 v[120:123], v[140:143], v[196:199], v[120:123]
	v_mfma_f32_16x16x32_bf16 v[112:115], v[24:27], v[204:207], v[112:115]
	v_mfma_f32_16x16x32_bf16 v[104:107], v[140:143], v[204:207], v[104:107]
	v_mfma_f32_16x16x32_bf16 v[96:99], v[24:27], v[216:219], v[96:99]
	v_mfma_f32_16x16x32_bf16 v[88:91], v[140:143], v[216:219], v[88:91]
	v_mfma_f32_16x16x32_bf16 v[136:139], v[32:35], v[192:195], v[136:139]
	v_mfma_f32_16x16x32_bf16 v[132:135], v[144:147], v[192:195], v[132:135]
	v_mfma_f32_16x16x32_bf16 v[128:131], v[32:35], v[200:203], v[128:131]
	v_mfma_f32_16x16x32_bf16 v[120:123], v[144:147], v[200:203], v[120:123]
	v_mfma_f32_16x16x32_bf16 v[112:115], v[32:35], v[212:215], v[112:115]
	v_mfma_f32_16x16x32_bf16 v[104:107], v[144:147], v[212:215], v[104:107]
	v_mfma_f32_16x16x32_bf16 v[96:99], v[32:35], v[220:223], v[96:99]
	v_mfma_f32_16x16x32_bf16 v[88:91], v[144:147], v[220:223], v[88:91]
	v_mfma_f32_16x16x32_bf16 v[124:127], v[172:175], v[188:191], v[124:127]
	v_mfma_f32_16x16x32_bf16 v[116:119], v[180:183], v[188:191], v[116:119]
	v_mfma_f32_16x16x32_bf16 v[108:111], v[172:175], v[196:199], v[108:111]
	v_mfma_f32_16x16x32_bf16 v[100:103], v[180:183], v[196:199], v[100:103]
	v_mfma_f32_16x16x32_bf16 v[92:95], v[172:175], v[204:207], v[92:95]
	v_mfma_f32_16x16x32_bf16 v[84:87], v[180:183], v[204:207], v[84:87]
	v_mfma_f32_16x16x32_bf16 v[80:83], v[172:175], v[216:219], v[80:83]
	v_mfma_f32_16x16x32_bf16 v[76:79], v[180:183], v[216:219], v[76:79]
	v_mfma_f32_16x16x32_bf16 v[124:127], v[176:179], v[192:195], v[124:127]
	v_mfma_f32_16x16x32_bf16 v[116:119], v[184:187], v[192:195], v[116:119]
	v_mfma_f32_16x16x32_bf16 v[108:111], v[176:179], v[200:203], v[108:111]
	v_mfma_f32_16x16x32_bf16 v[100:103], v[184:187], v[200:203], v[100:103]
	v_mfma_f32_16x16x32_bf16 v[92:95], v[176:179], v[212:215], v[92:95]
	v_mfma_f32_16x16x32_bf16 v[84:87], v[184:187], v[212:215], v[84:87]
	v_mfma_f32_16x16x32_bf16 v[80:83], v[176:179], v[220:223], v[80:83]
	v_mfma_f32_16x16x32_bf16 v[76:79], v[184:187], v[220:223], v[76:79]
	s_barrier
	s_setprio 0
	s_add_i32 s34, s53, s7
	s_mov_b32 m0, s34
	ds_read_b128 v[188:191], v170 offset:49152
	ds_read_b128 v[192:195], v170 offset:50176
	ds_read_b128 v[196:199], v170 offset:51200
	ds_read_b128 v[200:203], v170 offset:52224
	ds_read_b128 v[204:207], v170 offset:53248
	ds_read_b128 v[212:215], v170 offset:54272
	ds_read_b128 v[216:219], v170 offset:55296
	ds_read_b128 v[220:223], v170 offset:56320
	global_load_lds_dwordx4 v2, s[98:99]
	s_add_i32 m0, s34, 0x2000
	s_add_u32 s26, s26, 0x80080
	s_addc_u32 s27, s27, 0
	s_add_i32 s34, s54, s7
	global_load_lds_dwordx4 v148, s[98:99]
	s_mov_b32 m0, s34
	s_nop 0
	global_load_lds_dwordx4 v2, s[26:27]
	s_add_i32 m0, s34, 0x2000
	s_nop 0
	global_load_lds_dwordx4 v148, s[26:27]
	s_mov_b32 m0, s49
	s_nop 0
	global_load_lds_dwordx4 v152, s[100:101]
	s_mov_b32 m0, s50
	s_nop 0
	global_load_lds_dwordx4 v150, s[100:101]
	s_waitcnt vmcnt(8)
	s_waitcnt lgkmcnt(0)
	s_setprio 1
	s_barrier
	v_mfma_f32_16x16x32_bf16 v[72:75], v[24:27], v[188:191], v[72:75]
	v_mfma_f32_16x16x32_bf16 v[64:67], v[24:27], v[196:199], v[64:67]
	v_mfma_f32_16x16x32_bf16 v[48:51], v[24:27], v[204:207], v[48:51]
	v_mfma_f32_16x16x32_bf16 v[4:7], v[24:27], v[216:219], v[4:7]
	v_mfma_f32_16x16x32_bf16 v[72:75], v[32:35], v[192:195], v[72:75]
	v_mfma_f32_16x16x32_bf16 v[68:71], v[140:143], v[188:191], v[68:71]
	v_mfma_f32_16x16x32_bf16 v[64:67], v[32:35], v[200:203], v[64:67]
	v_mfma_f32_16x16x32_bf16 v[56:59], v[140:143], v[196:199], v[56:59]
	v_mfma_f32_16x16x32_bf16 v[48:51], v[32:35], v[212:215], v[48:51]
	v_mfma_f32_16x16x32_bf16 v[40:43], v[140:143], v[204:207], v[40:43]
	v_mfma_f32_16x16x32_bf16 v[32:35], v[32:35], v[220:223], v[4:7]
	v_mfma_f32_16x16x32_bf16 v[4:7], v[140:143], v[216:219], v[8:11]
	v_mfma_f32_16x16x32_bf16 v[68:71], v[144:147], v[192:195], v[68:71]
	v_mfma_f32_16x16x32_bf16 v[56:59], v[144:147], v[200:203], v[56:59]
	v_mfma_f32_16x16x32_bf16 v[40:43], v[144:147], v[212:215], v[40:43]
	v_mfma_f32_16x16x32_bf16 v[24:27], v[144:147], v[220:223], v[4:7]
	v_mfma_f32_16x16x32_bf16 v[4:7], v[172:175], v[188:191], v[60:63]
	v_mfma_f32_16x16x32_bf16 v[60:63], v[176:179], v[192:195], v[4:7]
	v_mfma_f32_16x16x32_bf16 v[4:7], v[180:183], v[188:191], v[52:55]
	v_mfma_f32_16x16x32_bf16 v[52:55], v[184:187], v[192:195], v[4:7]
	v_mfma_f32_16x16x32_bf16 v[4:7], v[172:175], v[196:199], v[44:47]
	v_mfma_f32_16x16x32_bf16 v[44:47], v[176:179], v[200:203], v[4:7]
	v_mfma_f32_16x16x32_bf16 v[4:7], v[180:183], v[196:199], v[36:39]
	v_mfma_f32_16x16x32_bf16 v[36:39], v[184:187], v[200:203], v[4:7]
	v_mfma_f32_16x16x32_bf16 v[4:7], v[172:175], v[204:207], v[28:31]
	v_mfma_f32_16x16x32_bf16 v[28:31], v[176:179], v[212:215], v[4:7]
	v_mfma_f32_16x16x32_bf16 v[4:7], v[180:183], v[204:207], v[20:23]
	v_mfma_f32_16x16x32_bf16 v[20:23], v[184:187], v[212:215], v[4:7]
	v_mfma_f32_16x16x32_bf16 v[4:7], v[172:175], v[216:219], v[16:19]
	v_mfma_f32_16x16x32_bf16 v[16:19], v[176:179], v[220:223], v[4:7]
	v_mfma_f32_16x16x32_bf16 v[4:7], v[180:183], v[216:219], v[12:15]
	v_mfma_f32_16x16x32_bf16 v[12:15], v[184:187], v[220:223], v[4:7]
	s_barrier
	s_setprio 0
	s_add_i32 s33, s33, 2
	s_add_u32 s22, s22, 0x1000
	s_addc_u32 s23, s23, 0
	s_add_u32 s15, s15, 0x100
	s_addc_u32 s17, s17, 0
	s_cmp_gt_u32 s33, 29
	s_cbranch_scc0 .LBB0_489
	s_branch .Lpeel_done_489
	.p2align	6

.LBB0_831:
	s_lshl_b32 s98, s100, 1
	s_add_u32 s2, s2, s100
	s_addc_u32 s3, s3, 0
	s_add_u32 s7, s22, 0x100
	s_addc_u32 s8, s23, 0
	s_mov_b32 s9, 0
	s_add_i32 s28, s9, 2
	s_add_u32 s22, s2, s100
	s_addc_u32 s23, s3, 0
	s_add_i32 s29, 0, 0x10000
	s_cmp_eq_u32 s52, s9
	s_cselect_b32 s23, s1, s23
	s_cselect_b32 s22, s0, s22
	v_add_u32_e32 v2, s29, v147
	s_cselect_b32 s35, s21, s8
	s_cselect_b32 s34, s20, s7
	s_add_i32 s9, 0, 0x14000
	ds_read_b128 v[152:155], v2
	ds_read_b128 v[156:159], v2 offset:1024
	ds_read_b128 v[160:163], v2 offset:2048
	ds_read_b128 v[168:171], v2 offset:3072
	v_add_u32_e32 v2, s9, v147
	ds_read_b128 v[172:175], v2
	ds_read_b128 v[176:179], v2 offset:1024
	ds_read_b128 v[180:183], v2 offset:2048
	ds_read_b128 v[184:187], v2 offset:3072
	s_add_i32 m0, s47, 0xc000
	ds_read_b128 v[188:191], v150
	ds_read_b128 v[192:195], v150 offset:1024
	ds_read_b128 v[196:199], v150 offset:2048
	ds_read_b128 v[200:203], v150 offset:3072
	ds_read_b128 v[204:207], v150 offset:4096
	ds_read_b128 v[210:213], v150 offset:5120
	ds_read_b128 v[214:217], v150 offset:6144
	ds_read_b128 v[218:221], v150 offset:7168
	global_load_lds_dwordx4 v140, s[2:3]
	s_add_i32 m0, s47, 0xe000
	s_nop 0
	global_load_lds_dwordx4 v142, s[2:3]
	s_waitcnt vmcnt(8)
	s_waitcnt lgkmcnt(0)
	s_setprio 1
	s_barrier
	v_mfma_f32_16x16x32_bf16 v[128:131], v[152:155], v[188:191], 0
	v_mfma_f32_16x16x32_bf16 v[124:127], v[160:163], v[188:191], 0
	v_mfma_f32_16x16x32_bf16 v[112:115], v[152:155], v[196:199], 0
	v_mfma_f32_16x16x32_bf16 v[108:111], v[160:163], v[196:199], 0
	v_mfma_f32_16x16x32_bf16 v[96:99], v[152:155], v[204:207], 0
	v_mfma_f32_16x16x32_bf16 v[92:95], v[160:163], v[204:207], 0
	v_mfma_f32_16x16x32_bf16 v[80:83], v[152:155], v[214:217], 0
	v_mfma_f32_16x16x32_bf16 v[76:79], v[160:163], v[214:217], 0
	v_mfma_f32_16x16x32_bf16 v[128:131], v[156:159], v[192:195], v[128:131]
	v_mfma_f32_16x16x32_bf16 v[124:127], v[168:171], v[192:195], v[124:127]
	v_mfma_f32_16x16x32_bf16 v[112:115], v[156:159], v[200:203], v[112:115]
	v_mfma_f32_16x16x32_bf16 v[108:111], v[168:171], v[200:203], v[108:111]
	v_mfma_f32_16x16x32_bf16 v[96:99], v[156:159], v[210:213], v[96:99]
	v_mfma_f32_16x16x32_bf16 v[92:95], v[168:171], v[210:213], v[92:95]
	v_mfma_f32_16x16x32_bf16 v[80:83], v[156:159], v[218:221], v[80:83]
	v_mfma_f32_16x16x32_bf16 v[76:79], v[168:171], v[218:221], v[76:79]
	v_mfma_f32_16x16x32_bf16 v[120:123], v[172:175], v[188:191], 0
	v_mfma_f32_16x16x32_bf16 v[116:119], v[180:183], v[188:191], 0
	v_mfma_f32_16x16x32_bf16 v[104:107], v[172:175], v[196:199], 0
	v_mfma_f32_16x16x32_bf16 v[100:103], v[180:183], v[196:199], 0
	v_mfma_f32_16x16x32_bf16 v[88:91], v[172:175], v[204:207], 0
	v_mfma_f32_16x16x32_bf16 v[84:87], v[180:183], v[204:207], 0
	v_mfma_f32_16x16x32_bf16 v[72:75], v[172:175], v[214:217], 0
	v_mfma_f32_16x16x32_bf16 v[68:71], v[180:183], v[214:217], 0
	v_mfma_f32_16x16x32_bf16 v[120:123], v[176:179], v[192:195], v[120:123]
	v_mfma_f32_16x16x32_bf16 v[116:119], v[184:187], v[192:195], v[116:119]
	v_mfma_f32_16x16x32_bf16 v[104:107], v[176:179], v[200:203], v[104:107]
	v_mfma_f32_16x16x32_bf16 v[100:103], v[184:187], v[200:203], v[100:103]
	v_mfma_f32_16x16x32_bf16 v[88:91], v[176:179], v[210:213], v[88:91]
	v_mfma_f32_16x16x32_bf16 v[84:87], v[184:187], v[210:213], v[84:87]
	v_mfma_f32_16x16x32_bf16 v[72:75], v[176:179], v[218:221], v[72:75]
	v_mfma_f32_16x16x32_bf16 v[68:71], v[184:187], v[218:221], v[68:71]
	s_barrier
	s_setprio 0
	s_add_i32 s29, s29, s26
	s_mov_b32 m0, s29
	ds_read_b128 v[188:191], v150 offset:16384
	ds_read_b128 v[192:195], v150 offset:17408
	ds_read_b128 v[196:199], v150 offset:18432
	ds_read_b128 v[200:203], v150 offset:19456
	ds_read_b128 v[204:207], v150 offset:20480
	ds_read_b128 v[210:213], v150 offset:21504
	ds_read_b128 v[214:217], v150 offset:22528
	ds_read_b128 v[218:221], v150 offset:23552
	global_load_lds_dwordx4 v136, s[34:35]
	s_add_i32 m0, s29, 0x2000
	s_add_i32 s9, s9, s26
	global_load_lds_dwordx4 v132, s[34:35]
	s_add_u32 s34, s34, s16
	s_addc_u32 s35, s35, 0
	s_mov_b32 m0, s9
	s_nop 0
	global_load_lds_dwordx4 v136, s[34:35]
	s_add_i32 m0, s9, 0x2000
	s_nop 0
	global_load_lds_dwordx4 v132, s[34:35]
	s_mov_b32 m0, s47
	s_nop 0
	global_load_lds_dwordx4 v138, s[22:23]
	s_mov_b32 m0, s48
	s_nop 0
	global_load_lds_dwordx4 v134, s[22:23]
	s_waitcnt vmcnt(8)
	s_waitcnt lgkmcnt(0)
	s_setprio 1
	s_barrier
	v_mfma_f32_16x16x32_bf16 v[64:67], v[152:155], v[188:191], 0
	v_mfma_f32_16x16x32_bf16 v[60:63], v[160:163], v[188:191], 0
	v_mfma_f32_16x16x32_bf16 v[48:51], v[152:155], v[196:199], 0
	v_mfma_f32_16x16x32_bf16 v[44:47], v[160:163], v[196:199], 0
	v_mfma_f32_16x16x32_bf16 v[32:35], v[152:155], v[204:207], 0
	v_mfma_f32_16x16x32_bf16 v[28:31], v[160:163], v[204:207], 0
	v_mfma_f32_16x16x32_bf16 v[16:19], v[152:155], v[214:217], 0
	v_mfma_f32_16x16x32_bf16 v[12:15], v[160:163], v[214:217], 0
	v_mfma_f32_16x16x32_bf16 v[64:67], v[156:159], v[192:195], v[64:67]
	v_mfma_f32_16x16x32_bf16 v[60:63], v[168:171], v[192:195], v[60:63]
	v_mfma_f32_16x16x32_bf16 v[48:51], v[156:159], v[200:203], v[48:51]
	v_mfma_f32_16x16x32_bf16 v[44:47], v[168:171], v[200:203], v[44:47]
	v_mfma_f32_16x16x32_bf16 v[32:35], v[156:159], v[210:213], v[32:35]
	v_mfma_f32_16x16x32_bf16 v[28:31], v[168:171], v[210:213], v[28:31]
	v_mfma_f32_16x16x32_bf16 v[16:19], v[156:159], v[218:221], v[16:19]
	v_mfma_f32_16x16x32_bf16 v[12:15], v[168:171], v[218:221], v[12:15]
	v_mfma_f32_16x16x32_bf16 v[56:59], v[172:175], v[188:191], 0
	v_mfma_f32_16x16x32_bf16 v[52:55], v[180:183], v[188:191], 0
	v_mfma_f32_16x16x32_bf16 v[40:43], v[172:175], v[196:199], 0
	v_mfma_f32_16x16x32_bf16 v[36:39], v[180:183], v[196:199], 0
	v_mfma_f32_16x16x32_bf16 v[24:27], v[172:175], v[204:207], 0
	v_mfma_f32_16x16x32_bf16 v[20:23], v[180:183], v[204:207], 0
	v_mfma_f32_16x16x32_bf16 v[8:11], v[172:175], v[214:217], 0
	v_mfma_f32_16x16x32_bf16 v[4:7], v[180:183], v[214:217], 0
	v_mfma_f32_16x16x32_bf16 v[56:59], v[176:179], v[192:195], v[56:59]
	v_mfma_f32_16x16x32_bf16 v[52:55], v[184:187], v[192:195], v[52:55]
	v_mfma_f32_16x16x32_bf16 v[40:43], v[176:179], v[200:203], v[40:43]
	v_mfma_f32_16x16x32_bf16 v[36:39], v[184:187], v[200:203], v[36:39]
	v_mfma_f32_16x16x32_bf16 v[24:27], v[176:179], v[210:213], v[24:27]
	v_mfma_f32_16x16x32_bf16 v[20:23], v[184:187], v[210:213], v[20:23]
	v_mfma_f32_16x16x32_bf16 v[8:11], v[176:179], v[218:221], v[8:11]
	v_mfma_f32_16x16x32_bf16 v[4:7], v[184:187], v[218:221], v[4:7]
	s_barrier
	s_setprio 0
	s_add_i32 s9, 0, 0x18000
	v_add_u32_e32 v2, s9, v147
	s_add_i32 s29, 0, 0x1c000
	ds_read_b128 v[152:155], v2
	ds_read_b128 v[156:159], v2 offset:1024
	ds_read_b128 v[160:163], v2 offset:2048
	ds_read_b128 v[168:171], v2 offset:3072
	v_add_u32_e32 v2, s29, v147
	ds_read_b128 v[172:175], v2
	ds_read_b128 v[176:179], v2 offset:1024
	ds_read_b128 v[180:183], v2 offset:2048
	ds_read_b128 v[184:187], v2 offset:3072
	s_add_u32 s22, s22, s16
	s_addc_u32 s23, s23, 0
	s_mov_b32 m0, s49
	ds_read_b128 v[188:191], v150 offset:32768
	ds_read_b128 v[192:195], v150 offset:33792
	ds_read_b128 v[196:199], v150 offset:34816
	ds_read_b128 v[200:203], v150 offset:35840
	ds_read_b128 v[204:207], v150 offset:36864
	ds_read_b128 v[210:213], v150 offset:37888
	ds_read_b128 v[214:217], v150 offset:38912
	ds_read_b128 v[218:221], v150 offset:39936
	global_load_lds_dwordx4 v138, s[22:23]
	s_mov_b32 m0, s50
	s_nop 0
	global_load_lds_dwordx4 v134, s[22:23]
	s_waitcnt vmcnt(8)
	s_waitcnt lgkmcnt(0)
	s_setprio 1
	s_barrier
	v_mfma_f32_16x16x32_bf16 v[128:131], v[152:155], v[188:191], v[128:131]
	v_mfma_f32_16x16x32_bf16 v[124:127], v[160:163], v[188:191], v[124:127]
	v_mfma_f32_16x16x32_bf16 v[112:115], v[152:155], v[196:199], v[112:115]
	v_mfma_f32_16x16x32_bf16 v[108:111], v[160:163], v[196:199], v[108:111]
	v_mfma_f32_16x16x32_bf16 v[96:99], v[152:155], v[204:207], v[96:99]
	v_mfma_f32_16x16x32_bf16 v[92:95], v[160:163], v[204:207], v[92:95]
	v_mfma_f32_16x16x32_bf16 v[80:83], v[152:155], v[214:217], v[80:83]
	v_mfma_f32_16x16x32_bf16 v[76:79], v[160:163], v[214:217], v[76:79]
	v_mfma_f32_16x16x32_bf16 v[128:131], v[156:159], v[192:195], v[128:131]
	v_mfma_f32_16x16x32_bf16 v[124:127], v[168:171], v[192:195], v[124:127]
	v_mfma_f32_16x16x32_bf16 v[112:115], v[156:159], v[200:203], v[112:115]
	v_mfma_f32_16x16x32_bf16 v[108:111], v[168:171], v[200:203], v[108:111]
	v_mfma_f32_16x16x32_bf16 v[96:99], v[156:159], v[210:213], v[96:99]
	v_mfma_f32_16x16x32_bf16 v[92:95], v[168:171], v[210:213], v[92:95]
	v_mfma_f32_16x16x32_bf16 v[80:83], v[156:159], v[218:221], v[80:83]
	v_mfma_f32_16x16x32_bf16 v[76:79], v[168:171], v[218:221], v[76:79]
	v_mfma_f32_16x16x32_bf16 v[120:123], v[172:175], v[188:191], v[120:123]
	v_mfma_f32_16x16x32_bf16 v[116:119], v[180:183], v[188:191], v[116:119]
	v_mfma_f32_16x16x32_bf16 v[104:107], v[172:175], v[196:199], v[104:107]
	v_mfma_f32_16x16x32_bf16 v[100:103], v[180:183], v[196:199], v[100:103]
	v_mfma_f32_16x16x32_bf16 v[88:91], v[172:175], v[204:207], v[88:91]
	v_mfma_f32_16x16x32_bf16 v[84:87], v[180:183], v[204:207], v[84:87]
	v_mfma_f32_16x16x32_bf16 v[72:75], v[172:175], v[214:217], v[72:75]
	v_mfma_f32_16x16x32_bf16 v[68:71], v[180:183], v[214:217], v[68:71]
	v_mfma_f32_16x16x32_bf16 v[120:123], v[176:179], v[192:195], v[120:123]
	v_mfma_f32_16x16x32_bf16 v[116:119], v[184:187], v[192:195], v[116:119]
	v_mfma_f32_16x16x32_bf16 v[104:107], v[176:179], v[200:203], v[104:107]
	v_mfma_f32_16x16x32_bf16 v[100:103], v[184:187], v[200:203], v[100:103]
	v_mfma_f32_16x16x32_bf16 v[88:91], v[176:179], v[210:213], v[88:91]
	v_mfma_f32_16x16x32_bf16 v[84:87], v[184:187], v[210:213], v[84:87]
	v_mfma_f32_16x16x32_bf16 v[72:75], v[176:179], v[218:221], v[72:75]
	v_mfma_f32_16x16x32_bf16 v[68:71], v[184:187], v[218:221], v[68:71]
	s_barrier
	s_setprio 0
	s_add_i32 s9, s9, s26
	s_mov_b32 m0, s9
	ds_read_b128 v[188:191], v150 offset:49152
	ds_read_b128 v[192:195], v150 offset:50176
	ds_read_b128 v[196:199], v150 offset:51200
	ds_read_b128 v[200:203], v150 offset:52224
	ds_read_b128 v[204:207], v150 offset:53248
	ds_read_b128 v[210:213], v150 offset:54272
	ds_read_b128 v[214:217], v150 offset:55296
	ds_read_b128 v[218:221], v150 offset:56320
	s_sub_u32 s34, s34, s16
	s_subb_u32 s35, s35, 0
	s_add_u32 s34, s34, 0x80
	s_addc_u32 s35, s35, 0
	global_load_lds_dwordx4 v136, s[34:35]
	s_add_i32 m0, s9, 0x2000
	s_add_i32 s9, s29, s26
	global_load_lds_dwordx4 v132, s[34:35]
	s_mov_b32 m0, s9
	s_nop 0
	s_add_u32 s34, s34, s16
	s_addc_u32 s35, s35, 0
	global_load_lds_dwordx4 v136, s[34:35]
	s_add_i32 m0, s9, 0x2000
	s_nop 0
	global_load_lds_dwordx4 v132, s[34:35]
	s_mov_b32 m0, s53
	s_nop 0
	s_sub_u32 s22, s22, s16
	s_subb_u32 s23, s23, 0
	s_add_u32 s22, s22, s100
	s_addc_u32 s23, s23, 0
	global_load_lds_dwordx4 v138, s[22:23]
	s_mov_b32 m0, s54
	s_nop 0
	global_load_lds_dwordx4 v134, s[22:23]
	s_waitcnt vmcnt(8)
	s_waitcnt lgkmcnt(0)
	s_setprio 1
	s_barrier
	v_mfma_f32_16x16x32_bf16 v[64:67], v[152:155], v[188:191], v[64:67]
	v_mfma_f32_16x16x32_bf16 v[60:63], v[160:163], v[188:191], v[60:63]
	v_mfma_f32_16x16x32_bf16 v[48:51], v[152:155], v[196:199], v[48:51]
	v_mfma_f32_16x16x32_bf16 v[44:47], v[160:163], v[196:199], v[44:47]
	v_mfma_f32_16x16x32_bf16 v[32:35], v[152:155], v[204:207], v[32:35]
	v_mfma_f32_16x16x32_bf16 v[28:31], v[160:163], v[204:207], v[28:31]
	v_mfma_f32_16x16x32_bf16 v[16:19], v[152:155], v[214:217], v[16:19]
	v_mfma_f32_16x16x32_bf16 v[12:15], v[160:163], v[214:217], v[12:15]
	v_mfma_f32_16x16x32_bf16 v[64:67], v[156:159], v[192:195], v[64:67]
	v_mfma_f32_16x16x32_bf16 v[60:63], v[168:171], v[192:195], v[60:63]
	v_mfma_f32_16x16x32_bf16 v[48:51], v[156:159], v[200:203], v[48:51]
	v_mfma_f32_16x16x32_bf16 v[44:47], v[168:171], v[200:203], v[44:47]
	v_mfma_f32_16x16x32_bf16 v[32:35], v[156:159], v[210:213], v[32:35]
	v_mfma_f32_16x16x32_bf16 v[28:31], v[168:171], v[210:213], v[28:31]
	v_mfma_f32_16x16x32_bf16 v[16:19], v[156:159], v[218:221], v[16:19]
	v_mfma_f32_16x16x32_bf16 v[12:15], v[168:171], v[218:221], v[12:15]
	v_mfma_f32_16x16x32_bf16 v[56:59], v[172:175], v[188:191], v[56:59]
	v_mfma_f32_16x16x32_bf16 v[52:55], v[180:183], v[188:191], v[52:55]
	v_mfma_f32_16x16x32_bf16 v[40:43], v[172:175], v[196:199], v[40:43]
	v_mfma_f32_16x16x32_bf16 v[36:39], v[180:183], v[196:199], v[36:39]
	v_mfma_f32_16x16x32_bf16 v[24:27], v[172:175], v[204:207], v[24:27]
	v_mfma_f32_16x16x32_bf16 v[20:23], v[180:183], v[204:207], v[20:23]
	v_mfma_f32_16x16x32_bf16 v[8:11], v[172:175], v[214:217], v[8:11]
	v_mfma_f32_16x16x32_bf16 v[4:7], v[180:183], v[214:217], v[4:7]
	v_mfma_f32_16x16x32_bf16 v[56:59], v[176:179], v[192:195], v[56:59]
	v_mfma_f32_16x16x32_bf16 v[52:55], v[184:187], v[192:195], v[52:55]
	v_mfma_f32_16x16x32_bf16 v[40:43], v[176:179], v[200:203], v[40:43]
	v_mfma_f32_16x16x32_bf16 v[36:39], v[184:187], v[200:203], v[36:39]
	v_mfma_f32_16x16x32_bf16 v[24:27], v[176:179], v[210:213], v[24:27]
	v_mfma_f32_16x16x32_bf16 v[20:23], v[184:187], v[210:213], v[20:23]
	v_mfma_f32_16x16x32_bf16 v[8:11], v[176:179], v[218:221], v[8:11]
	v_mfma_f32_16x16x32_bf16 v[4:7], v[184:187], v[218:221], v[4:7]
	s_barrier
	s_setprio 0
	s_add_u32 s2, s2, s98
	s_addc_u32 s3, s3, 0
	s_add_u32 s7, s7, 0x100
	s_addc_u32 s8, s8, 0
	s_cmp_ge_u32 s28, s51
	s_mov_b32 s9, s28
	s_cbranch_scc0 .LBB0_832
	s_branch .Lpeel_done_832
	.p2align	6
